# NSA selected loop: K fragment ds_reads issued right after the tile barrier, tile-list entries prefetched one tile ahead (v116/v117)
# speedup vs baseline: 1.0008x; 1.0008x over previous
; DI void flash_init(Flash& st) { st.o0 = zero16(); st.o1 = zero16(); st.m = -1e20f; st.l = 0.f; }
; DI void nsa_item(const Params& p, char* sm, bool dec, int b, int kvh, int q32) {
;     ...
;         const int ntile = list[159];
;         Flash st; flash_init(st);
;         const OnFn onf{2, qvalid, (unsigned long long)s0 | ((unsigned long long)s1 << 32), (unsigned long long)s2 | ((unsigned long long)s3 << 32), cur};
;         if (dec) {
;             TileSrc src;
;             src.base = p.cache_n; src.pt = p.page_table; src.base_new = p.out + O_NKS;
;             src.P = 8192; src.ld = 512; src.newbs = 4; src.kcol = 256 + kvh * 64; src.vcol = 384 + kvh * 64; src.b = b; src.posoff = 0;
;             src.maxsrc = 8195;
;             run_tiles<0, 0>(st, qf, src, list, ntile, sm + SM_KV, qpos, qmin_w, qmax_w, onf, lut, bfar, nullptr, 0.f);
;         } else {
;             const size_t hb = (size_t)(b * 2 + kvh) * 8192 * 64;
;             const BSrc bs{(const u16*)(p.ws + WS_KSB) + hb, (const u16*)(p.ws + WS_VSB) + hb, 8191};
;             run_tiles_b<0, 0>(st, qf, bs, list, ntile, sm + SM_KV, qpos, qmin_w, qmax_w, onf, lut, bfar, nullptr, 0.f);
.LBB0_1360:
	s_andn2_b64 vcc, exec, s[0:1]
	v_sub_u32_e32 v179, v172, v195
	s_cbranch_vccnz .LBB0_1381
	v_lshlrev_b32_e32 v2, 1, v158
	v_mov_b32_e32 v16, v3
	v_mov_b32_e32 v17, v3
	v_lshl_add_u64 v[172:173], s[2:3], 0, v[2:3]
	v_lshl_add_u64 v[176:177], s[16:17], 0, v[2:3]
	v_mov_b32_e32 v2, v3
	v_mov_b32_e32 v4, v3
	v_mov_b32_e32 v5, v3
	v_mov_b32_e32 v6, v3
	v_mov_b32_e32 v7, v3
	v_mov_b32_e32 v8, v3
	v_mov_b32_e32 v9, v3
	v_mov_b32_e32 v10, v3
	v_mov_b32_e32 v11, v3
	v_mov_b32_e32 v12, v3
	v_mov_b32_e32 v13, v3
	v_mov_b32_e32 v14, v3
	v_mov_b32_e32 v15, v3
	v_mov_b64_e32 v[48:49], v[16:17]
	v_mov_b64_e32 v[32:33], v[16:17]
	s_add_i32 s16, 0, 0x8000
	v_mov_b32_e32 v169, 0
	v_mov_b32_e32 v181, 0xe0ad78ec
	s_mov_b32 s17, 3
	v_mov_b64_e32 v[46:47], v[14:15]
	v_mov_b64_e32 v[44:45], v[12:13]
	v_mov_b64_e32 v[42:43], v[10:11]
	v_mov_b64_e32 v[40:41], v[8:9]
	v_mov_b64_e32 v[38:39], v[6:7]
	v_mov_b64_e32 v[36:37], v[4:5]
	v_mov_b64_e32 v[34:35], v[2:3]
	v_mov_b64_e32 v[30:31], v[14:15]
	v_mov_b64_e32 v[28:29], v[12:13]
	v_mov_b64_e32 v[26:27], v[10:11]
	v_mov_b64_e32 v[24:25], v[8:9]
	v_mov_b64_e32 v[22:23], v[6:7]
	v_mov_b64_e32 v[20:21], v[4:5]
	v_mov_b64_e32 v[18:19], v[2:3]
	v_mov_b32_e32 v117, s16
	ds_read_b32 v116, v117
	ds_read_b32 v117, v117 offset:4
	s_branch .LBB0_1364

; template <int MASK, int PASS>
; DI void run_tiles_b(Flash& st, const bf16x8 (&qf)[4], const BSrc& src, const int* list, int n, char* kvbuf, int qpos,
;                     int qmin_w, int qmax_w, const OnFn onfn, const float* lut, float bfar, float* imp_row, float rinv) {
;     ...
;     for (int i = 0; i < n; i += 2) {
;         {
;             tileb_store(RA, kvbuf, kvbuf + 8192);
;             __syncthreads();
;             const int pos0 = list[i];
;             if (i + 2 < n) tileb_issue(RA, src, list[i + 2]);
.LBB0_1364:
	s_waitcnt vmcnt(0)
	s_waitcnt lgkmcnt(0)
	s_barrier
	ds_read_b128 v[50:53], v190
	ds_read_b128 v[138:141], v190 offset:4096
	ds_read_b128 v[150:153], v191
	ds_read_b128 v[12:15], v191 offset:4096
	ds_read_b128 v[146:149], v192
	ds_read_b128 v[8:11], v192 offset:4096
	ds_read_b128 v[142:145], v193
	ds_read_b128 v[4:7], v193 offset:4096
	s_add_i32 s21, s17, -1
	v_readfirstlane_b32 s22, v116
	s_add_i32 s0, s17, -2
	s_cmp_ge_i32 s0, s20
	s_cbranch_scc1 .LBB0_1366
	v_add_u32_e32 v120, v117, v118
	v_add_u32_e32 v122, v117, v119
	v_med3_i32 v120, v120, 0, v214
	v_med3_i32 v122, v122, 0, v214
	v_lshlrev_b32_e32 v120, 7, v120
	v_lshlrev_b32_e32 v122, 7, v122
	v_mov_b32_e32 v121, 0
	v_mov_b32_e32 v123, 0
	v_lshl_add_u64 v[124:125], v[110:111], 0, v[120:121]
	v_lshl_add_u64 v[126:127], v[112:113], 0, v[122:123]
	v_lshl_add_u64 v[128:129], v[114:115], 0, v[120:121]
	v_lshl_add_u64 v[130:131], v[114:115], 0, v[122:123]
	s_mov_b32 m0, s28
	s_add_i32 s58, s28, 0x400
	global_load_lds_dwordx4 v[124:125], off
	s_mov_b32 m0, s58
	s_nop 0
	global_load_lds_dwordx4 v[126:127], off
	s_mov_b32 m0, s32
	s_add_i32 s58, s32, 0x400
	global_load_lds_dwordx4 v[128:129], off
	s_mov_b32 m0, s58
	s_nop 0
	global_load_lds_dwordx4 v[130:131], off
; DI float fexp2(float x) { return __builtin_amdgcn_exp2f(x); }
; DI f32x16 mfma32(bf16x8 a, bf16x8 b, f32x16 c) { return __builtin_amdgcn_mfma_f32_32x32x16_bf16(a, b, c, 0, 0, 0); }
; template <int MASK, bool NEAR, int PASS>
; DI void flash_tile(Flash& st, const bf16x8 (&qf)[4], const char* kbuf, const char* vbuf, int pos0, int qpos, bool on,
;                    const float* lut, float bfar, float* imp_row, float rinv) {
;     ...
; #pragma unroll
;     for (int ks = 0; ks < 4; ++ks) {
;         const int ka = r * 128 + (((2 * ks + h) ^ ((r >> 1) & 7)) << 4);
;         const bf16x8 a0 = *(const bf16x8*)(kbuf + ka);
;         const bf16x8 a1 = *(const bf16x8*)(kbuf + 4096 + ka);
;         s[0] = mfma32(a0, qf[ks], s[0]);
;         s[1] = mfma32(a1, qf[ks], s[1]);
;     }
;     constexpr float c1 = 0.125f * LOG2E;
;     float alpha = 1.f;
;     float rs = 0.f;
;     if (!NEAR) {
;         const float bc = MASK == 2 ? 0.f : bfar;
;         float mref;
;         if (PASS != 2) {
;             float mr = s[0][0];
; #pragma unroll
;             for (int i = 1; i < 16; ++i) mr = fmaxf(mr, s[0][i]);
; #pragma unroll
;             for (int i = 0; i < 16; ++i) mr = fmaxf(mr, s[1][i]);
;             float mx = on ? mr * c1 + bc : -1e30f;
;             mx = fmaxf(mx, __shfl_xor(mx, 32));
;             const float mnew = fmaxf(st.m, mx);
;             alpha = fexp2(st.m - mnew);
;             st.m = mnew;
;             mref = mnew;
;         } else mref = st.m;
;         float bm = on ? bc - mref : -1e30f;
;         if (PASS == 2) bm = on ? bm + __log2f(rinv) : -1e30f;
; #pragma unroll
;         for (int tt = 0; tt < 2; ++tt)
; #pragma unroll
;             for (int i = 0; i < 16; ++i) { const float pv = fexp2(s[tt][i] * c1 + bm); s[tt][i] = pv; rs += pv; }
;     DI bool operator()(int pos0) const {
;         if (kind == 0) return qvalid;
;         if (kind == 1) { const int blk = pos0 >> 8; return qvalid && (blk == cur || ((lo >> blk) & 1ull)); }
;         const int j = pos0 >> 6;
;         if (j >= 128) return qvalid;
;         const unsigned long long x = j < 64 ? lo : hi;
;         return qvalid && ((x >> (j & 63)) & 1ull) != 0ull;
;     }
.LBB0_1366:
	v_mov_b32_e32 v2, s16
	ds_read_b32 v116, v2 offset:4
	ds_read_b32 v117, v2 offset:8
	s_ashr_i32 s2, s22, 6
	s_cmpk_gt_i32 s2, 0x7f
	s_cselect_b64 vcc, -1, 0
	s_cmp_lt_i32 s2, 64
	s_cselect_b64 s[0:1], -1, 0
	v_cndmask_b32_e64 v121, v1, v157, s[0:1]
	v_cndmask_b32_e64 v120, v154, v174, s[0:1]
	v_lshrrev_b64 v[120:121], s2, v[120:121]
	v_and_b32_e32 v2, 1, v120
	v_cmp_eq_u32_e64 s[0:1], 1, v2
	s_and_b64 s[0:1], s[8:9], s[0:1]
	v_cndmask_b32_e64 v180, 0, 1, s[8:9]
	v_cndmask_b32_e64 v2, 0, 1, s[0:1]
	v_cndmask_b32_e32 v2, v2, v180, vcc
	v_and_b32_e32 v2, 1, v2
	v_cmp_eq_u32_e64 s[0:1], 1, v2
	v_cmp_ne_u32_e32 vcc, 0, v2
	s_cbranch_vccz .LBB0_1372
	s_add_i32 s2, s22, 0xb0
	v_cmp_le_i32_e32 vcc, s2, v226
	s_and_saveexec_b64 s[2:3], vcc
	s_xor_b64 s[2:3], exec, s[2:3]
	s_cbranch_execz .LBB0_1369
	s_waitcnt lgkmcnt(7)
	v_mfma_f32_32x32x16_bf16 v[66:81], v[50:53], v[94:97], 0
	s_waitcnt lgkmcnt(5)
	v_mfma_f32_32x32x16_bf16 v[66:81], v[150:153], v[98:101], v[66:81]
	v_mfma_f32_32x32x16_bf16 v[50:65], v[138:141], v[94:97], 0
	s_waitcnt lgkmcnt(3)
	v_mfma_f32_32x32x16_bf16 v[66:81], v[146:149], v[102:105], v[66:81]
	v_mfma_f32_32x32x16_bf16 v[50:65], v[12:15], v[98:101], v[50:65]
	s_waitcnt lgkmcnt(1)
	v_mfma_f32_32x32x16_bf16 v[66:81], v[142:145], v[106:109], v[66:81]
	v_mfma_f32_32x32x16_bf16 v[50:65], v[8:11], v[102:105], v[50:65]
	s_nop 10
	v_max3_f32 v2, v66, v67, v68
	v_max_f32_e32 v2, v2, v69
	v_max3_f32 v2, v2, v70, v71
	v_max3_f32 v2, v2, v72, v73
	v_max3_f32 v2, v2, v74, v75
	s_waitcnt lgkmcnt(0)
	v_mfma_f32_32x32x16_bf16 v[50:65], v[4:7], v[106:109], v[50:65]
	v_max3_f32 v2, v2, v76, v77
	v_max3_f32 v2, v2, v78, v79
	v_max3_f32 v2, v2, v80, v81
	s_nop 8
	v_max3_f32 v2, v2, v50, v51
	v_max3_f32 v2, v2, v52, v53
	v_max3_f32 v2, v2, v54, v55
	v_max3_f32 v2, v2, v56, v57
	v_max3_f32 v2, v2, v58, v59
	v_max3_f32 v2, v2, v60, v61
	v_max3_f32 v2, v2, v62, v63
	v_max3_f32 v2, v2, v64, v65
	v_fmamk_f32 v2, v2, 0x3e38aa3b, v225
	v_cndmask_b32_e64 v2, v215, v2, s[0:1]
	v_mov_b32_e32 v4, v2
	s_nop 1
	v_permlane32_swap_b32_e32 v2, v4
	v_max3_f32 v138, v181, v2, v4
	v_sub_f32_e32 v4, v138, v181
	v_cmp_lt_f32_e32 vcc, 0x41000000, v4
	s_nop 1
	v_cndmask_b32_e32 v138, v181, v138, vcc
	s_mov_b64 s[100:101], vcc
	v_sub_f32_e32 v4, v225, v138
	v_cndmask_b32_e64 v139, v215, v4, s[0:1]
	v_fmamk_f32 v4, v66, 0x3e38aa3b, v139
	v_exp_f32_e32 v8, v4
	v_fmamk_f32 v4, v67, 0x3e38aa3b, v139
	v_exp_f32_e32 v12, v4
	v_fmamk_f32 v4, v68, 0x3e38aa3b, v139
	v_exp_f32_e32 v9, v4
	v_fmamk_f32 v4, v69, 0x3e38aa3b, v139
	v_exp_f32_e32 v13, v4
	v_fmamk_f32 v4, v70, 0x3e38aa3b, v139
	v_exp_f32_e32 v10, v4
	v_fmamk_f32 v4, v71, 0x3e38aa3b, v139
	v_exp_f32_e32 v14, v4
	v_fmamk_f32 v4, v72, 0x3e38aa3b, v139
	v_exp_f32_e32 v11, v4
	v_fmamk_f32 v4, v73, 0x3e38aa3b, v139
	v_exp_f32_e32 v15, v4
	v_fmamk_f32 v4, v74, 0x3e38aa3b, v139
	v_exp_f32_e32 v66, v4
	v_fmamk_f32 v4, v75, 0x3e38aa3b, v139
	v_exp_f32_e32 v67, v4
	v_fmamk_f32 v4, v76, 0x3e38aa3b, v139
	v_exp_f32_e32 v68, v4
	v_fmamk_f32 v4, v77, 0x3e38aa3b, v139
	v_exp_f32_e32 v69, v4
	v_fmamk_f32 v4, v78, 0x3e38aa3b, v139
	v_exp_f32_e32 v70, v4
	v_fmamk_f32 v4, v79, 0x3e38aa3b, v139
	v_exp_f32_e32 v71, v4
	v_fmamk_f32 v4, v80, 0x3e38aa3b, v139
	v_exp_f32_e32 v72, v4
	v_add_f32_e32 v4, v12, v8
	v_add_f32_e32 v4, v9, v4
	v_add_f32_e32 v4, v13, v4
	v_add_f32_e32 v4, v10, v4
	v_add_f32_e32 v4, v14, v4
	v_add_f32_e32 v4, v11, v4
	v_add_f32_e32 v4, v15, v4
	v_add_f32_e32 v4, v66, v4
	v_add_f32_e32 v4, v67, v4
	v_fmamk_f32 v5, v81, 0x3e38aa3b, v139
	v_add_f32_e32 v4, v68, v4
	v_add_f32_e32 v4, v69, v4
	v_exp_f32_e32 v73, v5
	v_fmamk_f32 v5, v50, 0x3e38aa3b, v139
	v_add_f32_e32 v4, v70, v4
	v_exp_f32_e32 v50, v5
	v_fmamk_f32 v5, v51, 0x3e38aa3b, v139
	v_add_f32_e32 v4, v71, v4
	v_exp_f32_e32 v51, v5
	v_fmamk_f32 v5, v52, 0x3e38aa3b, v139
	v_add_f32_e32 v4, v72, v4
	v_exp_f32_e32 v52, v5
	v_fmamk_f32 v5, v53, 0x3e38aa3b, v139
	v_add_f32_e32 v4, v73, v4
	v_exp_f32_e32 v53, v5
	v_fmamk_f32 v5, v54, 0x3e38aa3b, v139
	v_add_f32_e32 v4, v50, v4
	v_exp_f32_e32 v54, v5
	v_fmamk_f32 v5, v55, 0x3e38aa3b, v139
	v_add_f32_e32 v4, v51, v4
	v_exp_f32_e32 v55, v5
	v_fmamk_f32 v5, v56, 0x3e38aa3b, v139
	v_add_f32_e32 v4, v52, v4
	v_exp_f32_e32 v56, v5
	v_fmamk_f32 v5, v57, 0x3e38aa3b, v139
	v_add_f32_e32 v4, v53, v4
	v_exp_f32_e32 v57, v5
	v_fmamk_f32 v5, v58, 0x3e38aa3b, v139
	v_add_f32_e32 v4, v54, v4
	v_exp_f32_e32 v58, v5
	v_fmamk_f32 v5, v59, 0x3e38aa3b, v139
	v_add_f32_e32 v4, v55, v4
	v_exp_f32_e32 v59, v5
	v_fmamk_f32 v5, v60, 0x3e38aa3b, v139
	v_add_f32_e32 v4, v56, v4
	v_exp_f32_e32 v60, v5
	v_add_f32_e32 v4, v57, v4
	v_add_f32_e32 v4, v58, v4
	v_add_f32_e32 v4, v59, v4
	v_sub_f32_e32 v2, v181, v138
	v_add_f32_e32 v74, v60, v4
	v_fmamk_f32 v4, v61, 0x3e38aa3b, v139
	v_exp_f32_e32 v2, v2
	v_exp_f32_e32 v61, v4
	ds_read_b64_tr_b16 v[4:5], v194 offset:8192
	ds_read_b64_tr_b16 v[6:7], v194 offset:9216
	v_cvt_pk_bf16_f32 v11, v11, v15
	v_cvt_pk_bf16_f32 v10, v10, v14
	v_cvt_pk_bf16_f32 v9, v9, v13
	v_cvt_pk_bf16_f32 v8, v8, v12
	ds_read_b64_tr_b16 v[14:15], v194 offset:9280
	ds_read_b64_tr_b16 v[12:13], v194 offset:8256
	s_cmp_eq_u64 s[100:101], 0
	s_cbranch_scc1 .Llz_selA
	v_pk_mul_f32 v[48:49], v[48:49], v[2:3] op_sel_hi:[1,0]
	v_pk_mul_f32 v[46:47], v[46:47], v[2:3] op_sel_hi:[1,0]
	v_pk_mul_f32 v[44:45], v[44:45], v[2:3] op_sel_hi:[1,0]
	v_pk_mul_f32 v[42:43], v[42:43], v[2:3] op_sel_hi:[1,0]
	v_pk_mul_f32 v[40:41], v[40:41], v[2:3] op_sel_hi:[1,0]
	v_pk_mul_f32 v[38:39], v[38:39], v[2:3] op_sel_hi:[1,0]
	v_pk_mul_f32 v[36:37], v[36:37], v[2:3] op_sel_hi:[1,0]
	v_pk_mul_f32 v[34:35], v[34:35], v[2:3] op_sel_hi:[1,0]
	v_pk_mul_f32 v[32:33], v[32:33], v[2:3] op_sel_hi:[1,0]
	v_pk_mul_f32 v[30:31], v[30:31], v[2:3] op_sel_hi:[1,0]
	v_pk_mul_f32 v[28:29], v[28:29], v[2:3] op_sel_hi:[1,0]
	v_pk_mul_f32 v[26:27], v[26:27], v[2:3] op_sel_hi:[1,0]
	v_pk_mul_f32 v[24:25], v[24:25], v[2:3] op_sel_hi:[1,0]
	v_pk_mul_f32 v[22:23], v[22:23], v[2:3] op_sel_hi:[1,0]
	v_pk_mul_f32 v[20:21], v[20:21], v[2:3] op_sel_hi:[1,0]
	v_pk_mul_f32 v[18:19], v[18:19], v[2:3] op_sel_hi:[1,0]

; template <int MASK, int PASS>
; DI void run_tiles_b(Flash& st, const bf16x8 (&qf)[4], const BSrc& src, const int* list, int n, char* kvbuf, int qpos,
;                     int qmin_w, int qmax_w, const OnFn onfn, const float* lut, float bfar, float* imp_row, float rinv) {
;     ...
;         if (i + 1 < n) {
;             tileb_store(RB, kvbuf + 16384, kvbuf + 24576);
;             __syncthreads();
;             const int pos0 = list[i + 1];
;             if (i + 3 < n) tileb_issue(RB, src, list[i + 3]);
.LBB0_1372:
	s_add_i32 s0, s17, -2
	s_cmp_ge_i32 s0, s20
	s_cbranch_scc1 .LBB0_1363
	s_waitcnt vmcnt(0)
	s_waitcnt lgkmcnt(0)
	s_barrier
	ds_read_b128 v[50:53], v190 offset:16384
	ds_read_b128 v[138:141], v190 offset:20480
	ds_read_b128 v[150:153], v191 offset:16384
	ds_read_b128 v[12:15], v191 offset:20480
	ds_read_b128 v[146:149], v192 offset:16384
	ds_read_b128 v[8:11], v192 offset:20480
	ds_read_b128 v[142:145], v193 offset:16384
	ds_read_b128 v[4:7], v193 offset:20480
	v_readfirstlane_b32 s22, v116
	s_cmp_ge_i32 s21, s20
	s_cbranch_scc1 .LBB0_1375
	v_add_u32_e32 v120, v117, v118
	v_add_u32_e32 v122, v117, v119
	v_med3_i32 v120, v120, 0, v214
	v_med3_i32 v122, v122, 0, v214
	v_lshlrev_b32_e32 v120, 7, v120
	v_lshlrev_b32_e32 v122, 7, v122
	v_mov_b32_e32 v121, 0
	v_mov_b32_e32 v123, 0
	v_lshl_add_u64 v[124:125], v[110:111], 0, v[120:121]
	v_lshl_add_u64 v[126:127], v[112:113], 0, v[122:123]
	v_lshl_add_u64 v[128:129], v[114:115], 0, v[120:121]
	v_lshl_add_u64 v[130:131], v[114:115], 0, v[122:123]
	s_mov_b32 m0, s24
	s_add_i32 s58, s24, 0x400
	global_load_lds_dwordx4 v[124:125], off
	s_mov_b32 m0, s58
	s_nop 0
	global_load_lds_dwordx4 v[126:127], off
	s_mov_b32 m0, s26
	s_add_i32 s58, s26, 0x400
	global_load_lds_dwordx4 v[128:129], off
	s_mov_b32 m0, s58
	s_nop 0
	global_load_lds_dwordx4 v[130:131], off
; DI float fexp2(float x) { return __builtin_amdgcn_exp2f(x); }
; DI f32x16 mfma32(bf16x8 a, bf16x8 b, f32x16 c) { return __builtin_amdgcn_mfma_f32_32x32x16_bf16(a, b, c, 0, 0, 0); }
; template <int MASK, bool NEAR, int PASS>
; DI void flash_tile(Flash& st, const bf16x8 (&qf)[4], const char* kbuf, const char* vbuf, int pos0, int qpos, bool on,
;                    const float* lut, float bfar, float* imp_row, float rinv) {
;     ...
; #pragma unroll
;     for (int ks = 0; ks < 4; ++ks) {
;         const int ka = r * 128 + (((2 * ks + h) ^ ((r >> 1) & 7)) << 4);
;         const bf16x8 a0 = *(const bf16x8*)(kbuf + ka);
;         const bf16x8 a1 = *(const bf16x8*)(kbuf + 4096 + ka);
;         s[0] = mfma32(a0, qf[ks], s[0]);
;         s[1] = mfma32(a1, qf[ks], s[1]);
;     }
;     constexpr float c1 = 0.125f * LOG2E;
;     float alpha = 1.f;
;     float rs = 0.f;
;     if (!NEAR) {
;         const float bc = MASK == 2 ? 0.f : bfar;
;         float mref;
;         if (PASS != 2) {
;             float mr = s[0][0];
; #pragma unroll
;             for (int i = 1; i < 16; ++i) mr = fmaxf(mr, s[0][i]);
; #pragma unroll
;             for (int i = 0; i < 16; ++i) mr = fmaxf(mr, s[1][i]);
;             float mx = on ? mr * c1 + bc : -1e30f;
;             mx = fmaxf(mx, __shfl_xor(mx, 32));
;             const float mnew = fmaxf(st.m, mx);
;             alpha = fexp2(st.m - mnew);
;             st.m = mnew;
;             mref = mnew;
;         } else mref = st.m;
;         float bm = on ? bc - mref : -1e30f;
;         if (PASS == 2) bm = on ? bm + __log2f(rinv) : -1e30f;
; #pragma unroll
;         for (int tt = 0; tt < 2; ++tt)
; #pragma unroll
;             for (int i = 0; i < 16; ++i) { const float pv = fexp2(s[tt][i] * c1 + bm); s[tt][i] = pv; rs += pv; }
;     DI bool operator()(int pos0) const {
;         if (kind == 0) return qvalid;
;         if (kind == 1) { const int blk = pos0 >> 8; return qvalid && (blk == cur || ((lo >> blk) & 1ull)); }
;         const int j = pos0 >> 6;
;         if (j >= 128) return qvalid;
;         const unsigned long long x = j < 64 ? lo : hi;
;         return qvalid && ((x >> (j & 63)) & 1ull) != 0ull;
;     }
.LBB0_1375:
	v_mov_b32_e32 v2, s16
	ds_read_b32 v116, v2 offset:8
	ds_read_b32 v117, v2 offset:12
	s_ashr_i32 s2, s22, 6
	s_cmpk_gt_i32 s2, 0x7f
	s_cselect_b64 vcc, -1, 0
	s_cmp_lt_i32 s2, 64
	s_cselect_b64 s[0:1], -1, 0
	v_cndmask_b32_e64 v121, v1, v157, s[0:1]
	v_cndmask_b32_e64 v120, v154, v174, s[0:1]
	v_lshrrev_b64 v[120:121], s2, v[120:121]
	v_and_b32_e32 v2, 1, v120
	v_cmp_eq_u32_e64 s[0:1], 1, v2
	s_and_b64 s[0:1], s[8:9], s[0:1]
	s_nop 0
	v_cndmask_b32_e64 v2, 0, 1, s[0:1]
	v_cndmask_b32_e32 v2, v2, v180, vcc
	v_and_b32_e32 v2, 1, v2
	v_cmp_eq_u32_e64 s[0:1], 1, v2
	v_cmp_ne_u32_e32 vcc, 0, v2
	s_cbranch_vccz .LBB0_1363
	s_add_i32 s2, s22, 0xb0
	v_cmp_le_i32_e32 vcc, s2, v226
	s_and_saveexec_b64 s[2:3], vcc
	s_xor_b64 s[2:3], exec, s[2:3]
	s_cbranch_execz .LBB0_1378
	s_waitcnt lgkmcnt(7)
	v_mfma_f32_32x32x16_bf16 v[66:81], v[50:53], v[94:97], 0
	s_waitcnt lgkmcnt(5)
	v_mfma_f32_32x32x16_bf16 v[66:81], v[150:153], v[98:101], v[66:81]
	v_mfma_f32_32x32x16_bf16 v[50:65], v[138:141], v[94:97], 0
	s_waitcnt lgkmcnt(3)
	v_mfma_f32_32x32x16_bf16 v[66:81], v[146:149], v[102:105], v[66:81]
	v_mfma_f32_32x32x16_bf16 v[50:65], v[12:15], v[98:101], v[50:65]
	s_waitcnt lgkmcnt(1)
	v_mfma_f32_32x32x16_bf16 v[66:81], v[142:145], v[106:109], v[66:81]
	v_mfma_f32_32x32x16_bf16 v[50:65], v[8:11], v[102:105], v[50:65]
	s_nop 10
	v_max3_f32 v2, v66, v67, v68
	v_max_f32_e32 v2, v2, v69
	v_max3_f32 v2, v2, v70, v71
	v_max3_f32 v2, v2, v72, v73
	v_max3_f32 v2, v2, v74, v75
	s_waitcnt lgkmcnt(0)
	v_mfma_f32_32x32x16_bf16 v[50:65], v[4:7], v[106:109], v[50:65]
	v_max3_f32 v2, v2, v76, v77
	v_max3_f32 v2, v2, v78, v79
	v_max3_f32 v2, v2, v80, v81
	s_nop 8
	v_max3_f32 v2, v2, v50, v51
	v_max3_f32 v2, v2, v52, v53
	v_max3_f32 v2, v2, v54, v55
	v_max3_f32 v2, v2, v56, v57
	v_max3_f32 v2, v2, v58, v59
	v_max3_f32 v2, v2, v60, v61
	v_max3_f32 v2, v2, v62, v63
	v_max3_f32 v2, v2, v64, v65
	v_fmamk_f32 v2, v2, 0x3e38aa3b, v225
	v_cndmask_b32_e64 v2, v215, v2, s[0:1]
	v_mov_b32_e32 v4, v2
	s_nop 1
	v_permlane32_swap_b32_e32 v2, v4
	v_max3_f32 v16, v181, v2, v4
	v_sub_f32_e32 v4, v16, v181
	v_cmp_lt_f32_e32 vcc, 0x41000000, v4
	s_nop 1
	v_cndmask_b32_e32 v16, v181, v16, vcc
	s_mov_b64 s[100:101], vcc
	v_sub_f32_e32 v4, v225, v16
	v_cndmask_b32_e64 v17, v215, v4, s[0:1]
	v_fmamk_f32 v4, v66, 0x3e38aa3b, v17
	v_exp_f32_e32 v8, v4
	v_fmamk_f32 v4, v67, 0x3e38aa3b, v17
	v_exp_f32_e32 v12, v4
	v_fmamk_f32 v4, v68, 0x3e38aa3b, v17
	v_exp_f32_e32 v9, v4
	v_fmamk_f32 v4, v69, 0x3e38aa3b, v17
	v_exp_f32_e32 v13, v4
	v_fmamk_f32 v4, v70, 0x3e38aa3b, v17
	v_exp_f32_e32 v10, v4
	v_fmamk_f32 v4, v71, 0x3e38aa3b, v17
	v_exp_f32_e32 v14, v4
	v_fmamk_f32 v4, v72, 0x3e38aa3b, v17
	v_exp_f32_e32 v11, v4
	v_fmamk_f32 v4, v73, 0x3e38aa3b, v17
	v_exp_f32_e32 v15, v4
	v_fmamk_f32 v4, v74, 0x3e38aa3b, v17
	v_exp_f32_e32 v66, v4
	v_fmamk_f32 v4, v75, 0x3e38aa3b, v17
	v_exp_f32_e32 v67, v4
	v_fmamk_f32 v4, v76, 0x3e38aa3b, v17
	v_exp_f32_e32 v68, v4
	v_fmamk_f32 v4, v77, 0x3e38aa3b, v17
	v_exp_f32_e32 v69, v4
	v_fmamk_f32 v4, v78, 0x3e38aa3b, v17
	v_exp_f32_e32 v70, v4
	v_fmamk_f32 v4, v79, 0x3e38aa3b, v17
	v_exp_f32_e32 v71, v4
	v_fmamk_f32 v4, v80, 0x3e38aa3b, v17
	v_exp_f32_e32 v72, v4
	v_add_f32_e32 v4, v12, v8
	v_add_f32_e32 v4, v9, v4
	v_add_f32_e32 v4, v13, v4
	v_add_f32_e32 v4, v10, v4
	v_add_f32_e32 v4, v14, v4
	v_add_f32_e32 v4, v11, v4
	v_add_f32_e32 v4, v15, v4
	v_add_f32_e32 v4, v66, v4
	v_add_f32_e32 v4, v67, v4
	v_fmamk_f32 v5, v81, 0x3e38aa3b, v17
	v_add_f32_e32 v4, v68, v4
	v_add_f32_e32 v4, v69, v4
	v_exp_f32_e32 v73, v5
	v_fmamk_f32 v5, v50, 0x3e38aa3b, v17
	v_add_f32_e32 v4, v70, v4
	v_exp_f32_e32 v50, v5
	v_fmamk_f32 v5, v51, 0x3e38aa3b, v17
	v_add_f32_e32 v4, v71, v4
	v_exp_f32_e32 v51, v5
	v_fmamk_f32 v5, v52, 0x3e38aa3b, v17
	v_add_f32_e32 v4, v72, v4
	v_exp_f32_e32 v52, v5
	v_fmamk_f32 v5, v53, 0x3e38aa3b, v17
	v_add_f32_e32 v4, v73, v4
	v_exp_f32_e32 v53, v5
	v_fmamk_f32 v5, v54, 0x3e38aa3b, v17
	v_add_f32_e32 v4, v50, v4
	v_exp_f32_e32 v54, v5
	v_fmamk_f32 v5, v55, 0x3e38aa3b, v17
	v_add_f32_e32 v4, v51, v4
	v_exp_f32_e32 v55, v5
	v_fmamk_f32 v5, v56, 0x3e38aa3b, v17
	v_add_f32_e32 v4, v52, v4
	v_exp_f32_e32 v56, v5
	v_fmamk_f32 v5, v57, 0x3e38aa3b, v17
	v_add_f32_e32 v4, v53, v4
	v_exp_f32_e32 v57, v5
	v_fmamk_f32 v5, v58, 0x3e38aa3b, v17
	v_add_f32_e32 v4, v54, v4
	v_exp_f32_e32 v58, v5
	v_fmamk_f32 v5, v59, 0x3e38aa3b, v17
	v_add_f32_e32 v4, v55, v4
	v_exp_f32_e32 v59, v5
	v_fmamk_f32 v5, v60, 0x3e38aa3b, v17
	v_add_f32_e32 v4, v56, v4
	v_exp_f32_e32 v60, v5
	v_add_f32_e32 v4, v57, v4
	v_add_f32_e32 v4, v58, v4
	v_add_f32_e32 v4, v59, v4
	v_sub_f32_e32 v2, v181, v16
	v_add_f32_e32 v74, v60, v4
	v_fmamk_f32 v4, v61, 0x3e38aa3b, v17
	v_exp_f32_e32 v2, v2
	v_exp_f32_e32 v61, v4
	ds_read_b64_tr_b16 v[4:5], v194 offset:24576
	ds_read_b64_tr_b16 v[6:7], v194 offset:25600
	v_cvt_pk_bf16_f32 v11, v11, v15
	v_cvt_pk_bf16_f32 v10, v10, v14
	v_cvt_pk_bf16_f32 v9, v9, v13
	v_cvt_pk_bf16_f32 v8, v8, v12
	ds_read_b64_tr_b16 v[14:15], v194 offset:25664
	ds_read_b64_tr_b16 v[12:13], v194 offset:24640
	s_cmp_eq_u64 s[100:101], 0
	s_cbranch_scc1 .Llz_selB
	v_pk_mul_f32 v[48:49], v[48:49], v[2:3] op_sel_hi:[1,0]
	v_pk_mul_f32 v[46:47], v[46:47], v[2:3] op_sel_hi:[1,0]
	v_pk_mul_f32 v[44:45], v[44:45], v[2:3] op_sel_hi:[1,0]
	v_pk_mul_f32 v[42:43], v[42:43], v[2:3] op_sel_hi:[1,0]
	v_pk_mul_f32 v[40:41], v[40:41], v[2:3] op_sel_hi:[1,0]
	v_pk_mul_f32 v[38:39], v[38:39], v[2:3] op_sel_hi:[1,0]
	v_pk_mul_f32 v[36:37], v[36:37], v[2:3] op_sel_hi:[1,0]
	v_pk_mul_f32 v[34:35], v[34:35], v[2:3] op_sel_hi:[1,0]
	v_pk_mul_f32 v[32:33], v[32:33], v[2:3] op_sel_hi:[1,0]
	v_pk_mul_f32 v[30:31], v[30:31], v[2:3] op_sel_hi:[1,0]
	v_pk_mul_f32 v[28:29], v[28:29], v[2:3] op_sel_hi:[1,0]
	v_pk_mul_f32 v[26:27], v[26:27], v[2:3] op_sel_hi:[1,0]
	v_pk_mul_f32 v[24:25], v[24:25], v[2:3] op_sel_hi:[1,0]
	v_pk_mul_f32 v[22:23], v[22:23], v[2:3] op_sel_hi:[1,0]
	v_pk_mul_f32 v[20:21], v[20:21], v[2:3] op_sel_hi:[1,0]
	v_pk_mul_f32 v[18:19], v[18:19], v[2:3] op_sel_hi:[1,0]

; DI void nsa_item(const Params& p, char* sm, bool dec, int b, int kvh, int q32) {
;     ...
;         const float rl = g1 / fmaxf(st.l, 1e-30f);
.LBB0_1380:
	s_waitcnt lgkmcnt(0)
	v_max_f32_e32 v1, v169, v169
	v_max_f32_e32 v1, 0xda24260, v1
	s_branch .LBB0_1382
